# FFN-up K-loops: first fragment read of the third load segment completed before the rest are issued (mirrors the first segment)
# speedup vs baseline: 1.0046x; 1.0046x over previous
.LBB0_1942:
	ds_read_b128 v[130:133], v200
	s_waitcnt lgkmcnt(0)
	ds_read_b128 v[134:137], v200 offset:1024
	ds_read_b128 v[138:141], v200 offset:2048
	ds_read_b128 v[142:145], v200 offset:3072
	ds_read_b128 v[146:149], v201
	ds_read_b128 v[150:153], v201 offset:1024
	ds_read_b128 v[154:157], v201 offset:2048
	ds_read_b128 v[158:161], v201 offset:3072
	s_add_u32 s26, s8, 0xfff80080
	s_addc_u32 s27, s9, -1
	s_cmp_eq_u32 s53, 28
	s_cselect_b32 s29, s7, s27
	s_cselect_b32 s28, s21, s26
	s_cselect_b32 s27, s19, s52
	s_cselect_b32 s26, s50, s51
	v_lshl_add_u64 v[216:217], s[8:9], 0, v[190:191]
	s_add_i32 m0, s35, 0xc000
	ds_read_b128 v[162:165], v202
	ds_read_b128 v[166:169], v202 offset:1024
	ds_read_b128 v[170:173], v202 offset:2048
	ds_read_b128 v[174:177], v202 offset:3072
	ds_read_b128 v[178:181], v202 offset:4096
	ds_read_b128 v[204:207], v202 offset:5120
	ds_read_b128 v[208:211], v202 offset:6144
	ds_read_b128 v[212:215], v202 offset:7168
	global_load_lds_dwordx4 v[216:217], off
	v_lshl_add_u64 v[216:217], s[8:9], 0, v[192:193]
	s_add_i32 m0, s35, 0xe000
	s_nop 0
	global_load_lds_dwordx4 v[216:217], off
	s_waitcnt vmcnt(8)
	s_waitcnt lgkmcnt(0)
	s_barrier
	s_setprio 1
	s_waitcnt lgkmcnt(0)
	v_mfma_f32_16x16x32_bf16 v[126:129], v[130:133], v[162:165], v[126:129]
	v_mfma_f32_16x16x32_bf16 v[122:125], v[138:141], v[162:165], v[122:125]
	v_mfma_f32_16x16x32_bf16 v[118:121], v[130:133], v[170:173], v[118:121]
	v_mfma_f32_16x16x32_bf16 v[110:113], v[138:141], v[170:173], v[110:113]
	v_mfma_f32_16x16x32_bf16 v[102:105], v[130:133], v[178:181], v[102:105]
	v_mfma_f32_16x16x32_bf16 v[94:97], v[138:141], v[178:181], v[94:97]
	v_mfma_f32_16x16x32_bf16 v[86:89], v[130:133], v[208:211], v[86:89]
	v_mfma_f32_16x16x32_bf16 v[78:81], v[138:141], v[208:211], v[78:81]
	v_mfma_f32_16x16x32_bf16 v[126:129], v[134:137], v[166:169], v[126:129]
	v_mfma_f32_16x16x32_bf16 v[122:125], v[142:145], v[166:169], v[122:125]
	v_mfma_f32_16x16x32_bf16 v[118:121], v[134:137], v[174:177], v[118:121]
	v_mfma_f32_16x16x32_bf16 v[110:113], v[142:145], v[174:177], v[110:113]
	v_mfma_f32_16x16x32_bf16 v[102:105], v[134:137], v[204:207], v[102:105]
	v_mfma_f32_16x16x32_bf16 v[94:97], v[142:145], v[204:207], v[94:97]
	v_mfma_f32_16x16x32_bf16 v[86:89], v[134:137], v[212:215], v[86:89]
	v_mfma_f32_16x16x32_bf16 v[78:81], v[142:145], v[212:215], v[78:81]
	s_setprio 0
	s_setprio 1
	v_mfma_f32_16x16x32_bf16 v[114:117], v[146:149], v[162:165], v[114:117]
	v_mfma_f32_16x16x32_bf16 v[106:109], v[154:157], v[162:165], v[106:109]
	v_mfma_f32_16x16x32_bf16 v[98:101], v[146:149], v[170:173], v[98:101]
	v_mfma_f32_16x16x32_bf16 v[90:93], v[154:157], v[170:173], v[90:93]
	v_mfma_f32_16x16x32_bf16 v[82:85], v[146:149], v[178:181], v[82:85]
	v_mfma_f32_16x16x32_bf16 v[74:77], v[154:157], v[178:181], v[74:77]
	v_mfma_f32_16x16x32_bf16 v[70:73], v[146:149], v[208:211], v[70:73]
	v_mfma_f32_16x16x32_bf16 v[66:69], v[154:157], v[208:211], v[66:69]
	v_mfma_f32_16x16x32_bf16 v[114:117], v[150:153], v[166:169], v[114:117]
	v_mfma_f32_16x16x32_bf16 v[106:109], v[158:161], v[166:169], v[106:109]
	v_mfma_f32_16x16x32_bf16 v[98:101], v[150:153], v[174:177], v[98:101]
	v_mfma_f32_16x16x32_bf16 v[90:93], v[158:161], v[174:177], v[90:93]
	v_mfma_f32_16x16x32_bf16 v[82:85], v[150:153], v[204:207], v[82:85]
	v_mfma_f32_16x16x32_bf16 v[74:77], v[158:161], v[204:207], v[74:77]
	v_mfma_f32_16x16x32_bf16 v[70:73], v[150:153], v[212:215], v[70:73]
	v_mfma_f32_16x16x32_bf16 v[66:69], v[158:161], v[212:215], v[66:69]
	s_setprio 0
	s_barrier
	s_add_i32 s54, s45, s31
	v_lshl_add_u64 v[216:217], s[26:27], 0, v[186:187]
	s_mov_b32 m0, s54
	ds_read_b128 v[162:165], v202 offset:16384
	ds_read_b128 v[166:169], v202 offset:17408
	ds_read_b128 v[170:173], v202 offset:18432
	ds_read_b128 v[174:177], v202 offset:19456
	ds_read_b128 v[178:181], v202 offset:20480
	ds_read_b128 v[204:207], v202 offset:21504
	ds_read_b128 v[208:211], v202 offset:22528
	ds_read_b128 v[212:215], v202 offset:23552
	global_load_lds_dwordx4 v[216:217], off
	s_add_i32 m0, s54, 0x2000
	s_add_u32 s54, s26, 0x80000
	v_lshl_add_u64 v[218:219], s[26:27], 0, v[182:183]
	s_addc_u32 s55, s27, 0
	s_add_i32 s56, s46, s31
	global_load_lds_dwordx4 v[218:219], off
	v_lshl_add_u64 v[220:221], s[54:55], 0, v[186:187]
	s_mov_b32 m0, s56
	v_lshl_add_u64 v[222:223], s[28:29], 0, v[184:185]
	global_load_lds_dwordx4 v[220:221], off
	v_lshl_add_u64 v[220:221], s[54:55], 0, v[182:183]
	s_add_i32 m0, s56, 0x2000
	s_nop 0
	global_load_lds_dwordx4 v[220:221], off
	v_lshl_add_u64 v[220:221], s[28:29], 0, v[188:189]
	s_mov_b32 m0, s35
	s_nop 0
	global_load_lds_dwordx4 v[220:221], off
	s_mov_b32 m0, s36
	s_nop 0
	global_load_lds_dwordx4 v[222:223], off
	s_waitcnt vmcnt(8)
	s_waitcnt lgkmcnt(0)
	s_barrier
	s_setprio 1
	s_waitcnt lgkmcnt(0)
	v_mfma_f32_16x16x32_bf16 v[62:65], v[130:133], v[162:165], v[62:65]
	v_mfma_f32_16x16x32_bf16 v[58:61], v[138:141], v[162:165], v[58:61]
	v_mfma_f32_16x16x32_bf16 v[54:57], v[130:133], v[170:173], v[54:57]
	v_mfma_f32_16x16x32_bf16 v[46:49], v[138:141], v[170:173], v[46:49]
	v_mfma_f32_16x16x32_bf16 v[38:41], v[130:133], v[178:181], v[38:41]
	v_mfma_f32_16x16x32_bf16 v[30:33], v[138:141], v[178:181], v[30:33]
	v_mfma_f32_16x16x32_bf16 v[22:25], v[130:133], v[208:211], v[22:25]
	v_mfma_f32_16x16x32_bf16 v[14:17], v[138:141], v[208:211], v[14:17]
	v_mfma_f32_16x16x32_bf16 v[62:65], v[134:137], v[166:169], v[62:65]
	v_mfma_f32_16x16x32_bf16 v[58:61], v[142:145], v[166:169], v[58:61]
	v_mfma_f32_16x16x32_bf16 v[54:57], v[134:137], v[174:177], v[54:57]
	v_mfma_f32_16x16x32_bf16 v[46:49], v[142:145], v[174:177], v[46:49]
	v_mfma_f32_16x16x32_bf16 v[38:41], v[134:137], v[204:207], v[38:41]
	v_mfma_f32_16x16x32_bf16 v[30:33], v[142:145], v[204:207], v[30:33]
	v_mfma_f32_16x16x32_bf16 v[22:25], v[134:137], v[212:215], v[22:25]
	v_mfma_f32_16x16x32_bf16 v[14:17], v[142:145], v[212:215], v[14:17]
	s_setprio 0
	s_setprio 1
	v_mfma_f32_16x16x32_bf16 v[50:53], v[146:149], v[162:165], v[50:53]
	v_mfma_f32_16x16x32_bf16 v[42:45], v[154:157], v[162:165], v[42:45]
	v_mfma_f32_16x16x32_bf16 v[34:37], v[146:149], v[170:173], v[34:37]
	v_mfma_f32_16x16x32_bf16 v[26:29], v[154:157], v[170:173], v[26:29]
	v_mfma_f32_16x16x32_bf16 v[18:21], v[146:149], v[178:181], v[18:21]
	v_mfma_f32_16x16x32_bf16 v[10:13], v[154:157], v[178:181], v[10:13]
	v_mfma_f32_16x16x32_bf16 v[6:9], v[146:149], v[208:211], v[6:9]
	v_mfma_f32_16x16x32_bf16 v[2:5], v[154:157], v[208:211], v[2:5]
	v_mfma_f32_16x16x32_bf16 v[50:53], v[150:153], v[166:169], v[50:53]
	v_mfma_f32_16x16x32_bf16 v[42:45], v[158:161], v[166:169], v[42:45]
	v_mfma_f32_16x16x32_bf16 v[34:37], v[150:153], v[174:177], v[34:37]
	v_mfma_f32_16x16x32_bf16 v[26:29], v[158:161], v[174:177], v[26:29]
	v_mfma_f32_16x16x32_bf16 v[18:21], v[150:153], v[204:207], v[18:21]
	v_mfma_f32_16x16x32_bf16 v[10:13], v[158:161], v[204:207], v[10:13]
	v_mfma_f32_16x16x32_bf16 v[6:9], v[150:153], v[212:215], v[6:9]
	v_mfma_f32_16x16x32_bf16 v[2:5], v[158:161], v[212:215], v[2:5]
	s_setprio 0
	s_barrier
	s_add_i32 s54, 0, 0x18000
	s_add_i32 s55, 0, 0x1c000
	v_add_u32_e32 v142, s54, v199
	v_add_u32_e32 v158, s55, v199
	ds_read_b128 v[130:133], v142
	s_waitcnt lgkmcnt(0)
	ds_read_b128 v[134:137], v142 offset:1024
	ds_read_b128 v[138:141], v142 offset:2048
	ds_read_b128 v[142:145], v142 offset:3072
	ds_read_b128 v[146:149], v158
	ds_read_b128 v[150:153], v158 offset:1024
	ds_read_b128 v[154:157], v158 offset:2048
	ds_read_b128 v[158:161], v158 offset:3072
	s_add_u32 s28, s28, 0x80000
	s_addc_u32 s29, s29, 0
	s_mov_b32 m0, s37
	v_lshl_add_u64 v[224:225], s[28:29], 0, v[188:189]
	ds_read_b128 v[162:165], v202 offset:32768
	ds_read_b128 v[166:169], v202 offset:33792
	ds_read_b128 v[170:173], v202 offset:34816
	ds_read_b128 v[174:177], v202 offset:35840
	ds_read_b128 v[178:181], v202 offset:36864
	ds_read_b128 v[204:207], v202 offset:37888
	ds_read_b128 v[208:211], v202 offset:38912
	ds_read_b128 v[212:215], v202 offset:39936
	global_load_lds_dwordx4 v[224:225], off
	v_lshl_add_u64 v[224:225], s[28:29], 0, v[184:185]
	s_mov_b32 m0, s38
	s_nop 0
	global_load_lds_dwordx4 v[224:225], off
	s_waitcnt vmcnt(8)
	s_waitcnt lgkmcnt(0)
	s_barrier
	s_setprio 1
	s_waitcnt lgkmcnt(0)
	v_mfma_f32_16x16x32_bf16 v[126:129], v[130:133], v[162:165], v[126:129]
	v_mfma_f32_16x16x32_bf16 v[122:125], v[138:141], v[162:165], v[122:125]
	v_mfma_f32_16x16x32_bf16 v[118:121], v[130:133], v[170:173], v[118:121]
	v_mfma_f32_16x16x32_bf16 v[110:113], v[138:141], v[170:173], v[110:113]
	v_mfma_f32_16x16x32_bf16 v[102:105], v[130:133], v[178:181], v[102:105]
	v_mfma_f32_16x16x32_bf16 v[94:97], v[138:141], v[178:181], v[94:97]
	v_mfma_f32_16x16x32_bf16 v[86:89], v[130:133], v[208:211], v[86:89]
	v_mfma_f32_16x16x32_bf16 v[78:81], v[138:141], v[208:211], v[78:81]
	v_mfma_f32_16x16x32_bf16 v[126:129], v[134:137], v[166:169], v[126:129]
	v_mfma_f32_16x16x32_bf16 v[122:125], v[142:145], v[166:169], v[122:125]
	v_mfma_f32_16x16x32_bf16 v[118:121], v[134:137], v[174:177], v[118:121]
	v_mfma_f32_16x16x32_bf16 v[110:113], v[142:145], v[174:177], v[110:113]
	v_mfma_f32_16x16x32_bf16 v[102:105], v[134:137], v[204:207], v[102:105]
	v_mfma_f32_16x16x32_bf16 v[94:97], v[142:145], v[204:207], v[94:97]
	v_mfma_f32_16x16x32_bf16 v[86:89], v[134:137], v[212:215], v[86:89]
	v_mfma_f32_16x16x32_bf16 v[78:81], v[142:145], v[212:215], v[78:81]
	s_setprio 0
	s_setprio 1
	v_mfma_f32_16x16x32_bf16 v[114:117], v[146:149], v[162:165], v[114:117]
	v_mfma_f32_16x16x32_bf16 v[106:109], v[154:157], v[162:165], v[106:109]
	v_mfma_f32_16x16x32_bf16 v[98:101], v[146:149], v[170:173], v[98:101]
	v_mfma_f32_16x16x32_bf16 v[90:93], v[154:157], v[170:173], v[90:93]
	v_mfma_f32_16x16x32_bf16 v[82:85], v[146:149], v[178:181], v[82:85]
	v_mfma_f32_16x16x32_bf16 v[74:77], v[154:157], v[178:181], v[74:77]
	v_mfma_f32_16x16x32_bf16 v[70:73], v[146:149], v[208:211], v[70:73]
	v_mfma_f32_16x16x32_bf16 v[66:69], v[154:157], v[208:211], v[66:69]
	v_mfma_f32_16x16x32_bf16 v[114:117], v[150:153], v[166:169], v[114:117]
	v_mfma_f32_16x16x32_bf16 v[106:109], v[158:161], v[166:169], v[106:109]
	v_mfma_f32_16x16x32_bf16 v[98:101], v[150:153], v[174:177], v[98:101]
	v_mfma_f32_16x16x32_bf16 v[90:93], v[158:161], v[174:177], v[90:93]
	v_mfma_f32_16x16x32_bf16 v[82:85], v[150:153], v[204:207], v[82:85]
	v_mfma_f32_16x16x32_bf16 v[74:77], v[158:161], v[204:207], v[74:77]
	v_mfma_f32_16x16x32_bf16 v[70:73], v[150:153], v[212:215], v[70:73]
	v_mfma_f32_16x16x32_bf16 v[66:69], v[158:161], v[212:215], v[66:69]
	s_setprio 0
	s_barrier
	s_add_i32 s28, s54, s31
	v_lshl_add_u64 v[216:217], v[216:217], 0, s[12:13]
	s_mov_b32 m0, s28
	ds_read_b128 v[162:165], v202 offset:49152
	ds_read_b128 v[166:169], v202 offset:50176
	ds_read_b128 v[170:173], v202 offset:51200
	ds_read_b128 v[174:177], v202 offset:52224
	ds_read_b128 v[178:181], v202 offset:53248
	ds_read_b128 v[204:207], v202 offset:54272
	ds_read_b128 v[208:211], v202 offset:55296
	ds_read_b128 v[212:215], v202 offset:56320
	global_load_lds_dwordx4 v[216:217], off
	s_add_i32 m0, s28, 0x2000
	s_add_u32 s26, s26, 0x80080
	v_lshl_add_u64 v[216:217], v[218:219], 0, s[12:13]
	s_addc_u32 s27, s27, 0
	s_add_i32 s28, s55, s31
	global_load_lds_dwordx4 v[216:217], off
	v_lshl_add_u64 v[216:217], s[26:27], 0, v[186:187]
	s_mov_b32 m0, s28
	s_nop 0
	global_load_lds_dwordx4 v[216:217], off
	v_lshl_add_u64 v[216:217], s[26:27], 0, v[182:183]
	s_add_i32 m0, s28, 0x2000
	s_nop 0
	global_load_lds_dwordx4 v[216:217], off
	v_lshl_add_u64 v[216:217], v[220:221], 0, s[12:13]
	s_mov_b32 m0, s42
	s_nop 0
	global_load_lds_dwordx4 v[216:217], off
	v_lshl_add_u64 v[216:217], v[222:223], 0, s[12:13]
	s_mov_b32 m0, s43
	s_nop 0
	global_load_lds_dwordx4 v[216:217], off
	s_waitcnt vmcnt(8)
	s_waitcnt lgkmcnt(0)
	s_barrier
	s_setprio 1
	s_waitcnt lgkmcnt(0)
	v_mfma_f32_16x16x32_bf16 v[62:65], v[130:133], v[162:165], v[62:65]
	v_mfma_f32_16x16x32_bf16 v[58:61], v[138:141], v[162:165], v[58:61]
	v_mfma_f32_16x16x32_bf16 v[54:57], v[130:133], v[170:173], v[54:57]
	v_mfma_f32_16x16x32_bf16 v[46:49], v[138:141], v[170:173], v[46:49]
	v_mfma_f32_16x16x32_bf16 v[38:41], v[130:133], v[178:181], v[38:41]
	v_mfma_f32_16x16x32_bf16 v[30:33], v[138:141], v[178:181], v[30:33]
	v_mfma_f32_16x16x32_bf16 v[22:25], v[130:133], v[208:211], v[22:25]
	v_mfma_f32_16x16x32_bf16 v[14:17], v[138:141], v[208:211], v[14:17]
	v_mfma_f32_16x16x32_bf16 v[62:65], v[134:137], v[166:169], v[62:65]
	v_mfma_f32_16x16x32_bf16 v[58:61], v[142:145], v[166:169], v[58:61]
	v_mfma_f32_16x16x32_bf16 v[54:57], v[134:137], v[174:177], v[54:57]
	v_mfma_f32_16x16x32_bf16 v[46:49], v[142:145], v[174:177], v[46:49]
	v_mfma_f32_16x16x32_bf16 v[38:41], v[134:137], v[204:207], v[38:41]
	v_mfma_f32_16x16x32_bf16 v[30:33], v[142:145], v[204:207], v[30:33]
	v_mfma_f32_16x16x32_bf16 v[22:25], v[134:137], v[212:215], v[22:25]
	v_mfma_f32_16x16x32_bf16 v[14:17], v[142:145], v[212:215], v[14:17]
	s_setprio 0
	s_setprio 1
	v_mfma_f32_16x16x32_bf16 v[50:53], v[146:149], v[162:165], v[50:53]
	v_mfma_f32_16x16x32_bf16 v[42:45], v[154:157], v[162:165], v[42:45]
	v_mfma_f32_16x16x32_bf16 v[34:37], v[146:149], v[170:173], v[34:37]
	v_mfma_f32_16x16x32_bf16 v[26:29], v[154:157], v[170:173], v[26:29]
	v_mfma_f32_16x16x32_bf16 v[18:21], v[146:149], v[178:181], v[18:21]
	v_mfma_f32_16x16x32_bf16 v[10:13], v[154:157], v[178:181], v[10:13]
	v_mfma_f32_16x16x32_bf16 v[6:9], v[146:149], v[208:211], v[6:9]
	v_mfma_f32_16x16x32_bf16 v[2:5], v[154:157], v[208:211], v[2:5]
	v_mfma_f32_16x16x32_bf16 v[50:53], v[150:153], v[166:169], v[50:53]
	v_mfma_f32_16x16x32_bf16 v[42:45], v[158:161], v[166:169], v[42:45]
	v_mfma_f32_16x16x32_bf16 v[34:37], v[150:153], v[174:177], v[34:37]
	v_mfma_f32_16x16x32_bf16 v[26:29], v[158:161], v[174:177], v[26:29]
	v_mfma_f32_16x16x32_bf16 v[18:21], v[150:153], v[204:207], v[18:21]
	v_mfma_f32_16x16x32_bf16 v[10:13], v[158:161], v[204:207], v[10:13]
	v_mfma_f32_16x16x32_bf16 v[6:9], v[150:153], v[212:215], v[6:9]
	v_mfma_f32_16x16x32_bf16 v[2:5], v[158:161], v[212:215], v[2:5]
	s_setprio 0
	s_barrier
	s_add_i32 s53, s53, 2
	s_add_u32 s8, s8, 0x100
	s_addc_u32 s9, s9, 0
	s_add_u32 s51, s51, 0x100
	s_addc_u32 s52, s52, 0
	s_cmp_gt_u32 s53, 29
	s_cbranch_scc0 .LBB0_1942
	s_and_b64 vcc, exec, s[14:15]
	s_cbranch_vccz .LBB0_1945
	s_barrier

.LBB0_3201:
	ds_read_b128 v[146:149], v164
	s_waitcnt lgkmcnt(0)
	ds_read_b128 v[150:153], v164 offset:1024
	ds_read_b128 v[154:157], v164 offset:2048
	ds_read_b128 v[158:161], v164 offset:3072
	ds_read_b128 v[168:171], v165
	ds_read_b128 v[172:175], v165 offset:1024
	ds_read_b128 v[176:179], v165 offset:2048
	ds_read_b128 v[180:183], v165 offset:3072
	s_add_u32 s40, s8, 0xfff80080
	s_addc_u32 s41, s9, -1
	s_cmp_eq_u32 s66, 28
	s_cselect_b32 s43, s7, s41
	s_cselect_b32 s42, s35, s40
	s_cselect_b32 s41, s31, s65
	s_cselect_b32 s40, s63, s64
	v_lshl_add_u64 v[216:217], s[8:9], 0, v[138:139]
	s_add_i32 m0, s46, 0xc000
	ds_read_b128 v[184:187], v166
	ds_read_b128 v[188:191], v166 offset:1024
	ds_read_b128 v[192:195], v166 offset:2048
	ds_read_b128 v[196:199], v166 offset:3072
	ds_read_b128 v[200:203], v166 offset:4096
	ds_read_b128 v[204:207], v166 offset:5120
	ds_read_b128 v[208:211], v166 offset:6144
	ds_read_b128 v[212:215], v166 offset:7168
	global_load_lds_dwordx4 v[216:217], off
	v_lshl_add_u64 v[216:217], s[8:9], 0, v[140:141]
	s_add_i32 m0, s46, 0xe000
	s_nop 0
	global_load_lds_dwordx4 v[216:217], off
	s_waitcnt vmcnt(8)
	s_waitcnt lgkmcnt(0)
	s_barrier
	s_setprio 1
	s_waitcnt lgkmcnt(0)
	v_mfma_f32_16x16x32_bf16 v[126:129], v[146:149], v[184:187], v[126:129]
	v_mfma_f32_16x16x32_bf16 v[122:125], v[154:157], v[184:187], v[122:125]
	v_mfma_f32_16x16x32_bf16 v[118:121], v[146:149], v[192:195], v[118:121]
	v_mfma_f32_16x16x32_bf16 v[110:113], v[154:157], v[192:195], v[110:113]
	v_mfma_f32_16x16x32_bf16 v[102:105], v[146:149], v[200:203], v[102:105]
	v_mfma_f32_16x16x32_bf16 v[94:97], v[154:157], v[200:203], v[94:97]
	v_mfma_f32_16x16x32_bf16 v[86:89], v[146:149], v[208:211], v[86:89]
	v_mfma_f32_16x16x32_bf16 v[78:81], v[154:157], v[208:211], v[78:81]
	v_mfma_f32_16x16x32_bf16 v[126:129], v[150:153], v[188:191], v[126:129]
	v_mfma_f32_16x16x32_bf16 v[122:125], v[158:161], v[188:191], v[122:125]
	v_mfma_f32_16x16x32_bf16 v[118:121], v[150:153], v[196:199], v[118:121]
	v_mfma_f32_16x16x32_bf16 v[110:113], v[158:161], v[196:199], v[110:113]
	v_mfma_f32_16x16x32_bf16 v[102:105], v[150:153], v[204:207], v[102:105]
	v_mfma_f32_16x16x32_bf16 v[94:97], v[158:161], v[204:207], v[94:97]
	v_mfma_f32_16x16x32_bf16 v[86:89], v[150:153], v[212:215], v[86:89]
	v_mfma_f32_16x16x32_bf16 v[78:81], v[158:161], v[212:215], v[78:81]
	s_setprio 0
	s_setprio 1
	v_mfma_f32_16x16x32_bf16 v[114:117], v[168:171], v[184:187], v[114:117]
	v_mfma_f32_16x16x32_bf16 v[106:109], v[176:179], v[184:187], v[106:109]
	v_mfma_f32_16x16x32_bf16 v[98:101], v[168:171], v[192:195], v[98:101]
	v_mfma_f32_16x16x32_bf16 v[90:93], v[176:179], v[192:195], v[90:93]
	v_mfma_f32_16x16x32_bf16 v[82:85], v[168:171], v[200:203], v[82:85]
	v_mfma_f32_16x16x32_bf16 v[74:77], v[176:179], v[200:203], v[74:77]
	v_mfma_f32_16x16x32_bf16 v[70:73], v[168:171], v[208:211], v[70:73]
	v_mfma_f32_16x16x32_bf16 v[66:69], v[176:179], v[208:211], v[66:69]
	v_mfma_f32_16x16x32_bf16 v[114:117], v[172:175], v[188:191], v[114:117]
	v_mfma_f32_16x16x32_bf16 v[106:109], v[180:183], v[188:191], v[106:109]
	v_mfma_f32_16x16x32_bf16 v[98:101], v[172:175], v[196:199], v[98:101]
	v_mfma_f32_16x16x32_bf16 v[90:93], v[180:183], v[196:199], v[90:93]
	v_mfma_f32_16x16x32_bf16 v[82:85], v[172:175], v[204:207], v[82:85]
	v_mfma_f32_16x16x32_bf16 v[74:77], v[180:183], v[204:207], v[74:77]
	v_mfma_f32_16x16x32_bf16 v[70:73], v[172:175], v[212:215], v[70:73]
	v_mfma_f32_16x16x32_bf16 v[66:69], v[180:183], v[212:215], v[66:69]
	s_setprio 0
	s_barrier
	s_add_i32 s67, s56, s33
	v_lshl_add_u64 v[216:217], s[40:41], 0, v[134:135]
	s_mov_b32 m0, s67
	ds_read_b128 v[184:187], v166 offset:16384
	ds_read_b128 v[188:191], v166 offset:17408
	ds_read_b128 v[192:195], v166 offset:18432
	ds_read_b128 v[196:199], v166 offset:19456
	ds_read_b128 v[200:203], v166 offset:20480
	ds_read_b128 v[204:207], v166 offset:21504
	ds_read_b128 v[208:211], v166 offset:22528
	ds_read_b128 v[212:215], v166 offset:23552
	global_load_lds_dwordx4 v[216:217], off
	s_add_i32 m0, s67, 0x2000
	s_add_u32 s68, s40, 0x80000
	v_lshl_add_u64 v[218:219], s[40:41], 0, v[130:131]
	s_addc_u32 s69, s41, 0
	s_add_i32 s67, s57, s33
	global_load_lds_dwordx4 v[218:219], off
	v_lshl_add_u64 v[220:221], s[68:69], 0, v[134:135]
	s_mov_b32 m0, s67
	v_lshl_add_u64 v[222:223], s[42:43], 0, v[132:133]
	global_load_lds_dwordx4 v[220:221], off
	v_lshl_add_u64 v[220:221], s[68:69], 0, v[130:131]
	s_add_i32 m0, s67, 0x2000
	s_nop 0
	global_load_lds_dwordx4 v[220:221], off
	v_lshl_add_u64 v[220:221], s[42:43], 0, v[136:137]
	s_mov_b32 m0, s46
	s_nop 0
	global_load_lds_dwordx4 v[220:221], off
	s_mov_b32 m0, s47
	s_nop 0
	global_load_lds_dwordx4 v[222:223], off
	s_waitcnt vmcnt(8)
	s_waitcnt lgkmcnt(0)
	s_barrier
	s_setprio 1
	s_waitcnt lgkmcnt(0)
	v_mfma_f32_16x16x32_bf16 v[62:65], v[146:149], v[184:187], v[62:65]
	v_mfma_f32_16x16x32_bf16 v[58:61], v[154:157], v[184:187], v[58:61]
	v_mfma_f32_16x16x32_bf16 v[54:57], v[146:149], v[192:195], v[54:57]
	v_mfma_f32_16x16x32_bf16 v[46:49], v[154:157], v[192:195], v[46:49]
	v_mfma_f32_16x16x32_bf16 v[38:41], v[146:149], v[200:203], v[38:41]
	v_mfma_f32_16x16x32_bf16 v[30:33], v[154:157], v[200:203], v[30:33]
	v_mfma_f32_16x16x32_bf16 v[22:25], v[146:149], v[208:211], v[22:25]
	v_mfma_f32_16x16x32_bf16 v[14:17], v[154:157], v[208:211], v[14:17]
	v_mfma_f32_16x16x32_bf16 v[62:65], v[150:153], v[188:191], v[62:65]
	v_mfma_f32_16x16x32_bf16 v[58:61], v[158:161], v[188:191], v[58:61]
	v_mfma_f32_16x16x32_bf16 v[54:57], v[150:153], v[196:199], v[54:57]
	v_mfma_f32_16x16x32_bf16 v[46:49], v[158:161], v[196:199], v[46:49]
	v_mfma_f32_16x16x32_bf16 v[38:41], v[150:153], v[204:207], v[38:41]
	v_mfma_f32_16x16x32_bf16 v[30:33], v[158:161], v[204:207], v[30:33]
	v_mfma_f32_16x16x32_bf16 v[22:25], v[150:153], v[212:215], v[22:25]
	v_mfma_f32_16x16x32_bf16 v[14:17], v[158:161], v[212:215], v[14:17]
	s_setprio 0
	s_setprio 1
	v_mfma_f32_16x16x32_bf16 v[50:53], v[168:171], v[184:187], v[50:53]
	v_mfma_f32_16x16x32_bf16 v[42:45], v[176:179], v[184:187], v[42:45]
	v_mfma_f32_16x16x32_bf16 v[34:37], v[168:171], v[192:195], v[34:37]
	v_mfma_f32_16x16x32_bf16 v[26:29], v[176:179], v[192:195], v[26:29]
	v_mfma_f32_16x16x32_bf16 v[18:21], v[168:171], v[200:203], v[18:21]
	v_mfma_f32_16x16x32_bf16 v[10:13], v[176:179], v[200:203], v[10:13]
	v_mfma_f32_16x16x32_bf16 v[6:9], v[168:171], v[208:211], v[6:9]
	v_mfma_f32_16x16x32_bf16 v[2:5], v[176:179], v[208:211], v[2:5]
	v_mfma_f32_16x16x32_bf16 v[50:53], v[172:175], v[188:191], v[50:53]
	v_mfma_f32_16x16x32_bf16 v[42:45], v[180:183], v[188:191], v[42:45]
	v_mfma_f32_16x16x32_bf16 v[34:37], v[172:175], v[196:199], v[34:37]
	v_mfma_f32_16x16x32_bf16 v[26:29], v[180:183], v[196:199], v[26:29]
	v_mfma_f32_16x16x32_bf16 v[18:21], v[172:175], v[204:207], v[18:21]
	v_mfma_f32_16x16x32_bf16 v[10:13], v[180:183], v[204:207], v[10:13]
	v_mfma_f32_16x16x32_bf16 v[6:9], v[172:175], v[212:215], v[6:9]
	v_mfma_f32_16x16x32_bf16 v[2:5], v[180:183], v[212:215], v[2:5]
	s_setprio 0
	s_barrier
	s_add_i32 s67, 0, 0x18000
	s_add_i32 s68, 0, 0x1c000
	v_add_u32_e32 v158, s67, v163
	v_add_u32_e32 v180, s68, v163
	ds_read_b128 v[146:149], v158
	s_waitcnt lgkmcnt(0)
	ds_read_b128 v[150:153], v158 offset:1024
	ds_read_b128 v[154:157], v158 offset:2048
	ds_read_b128 v[158:161], v158 offset:3072
	ds_read_b128 v[168:171], v180
	ds_read_b128 v[172:175], v180 offset:1024
	ds_read_b128 v[176:179], v180 offset:2048
	ds_read_b128 v[180:183], v180 offset:3072
	s_add_u32 s42, s42, 0x80000
	s_addc_u32 s43, s43, 0
	s_mov_b32 m0, s48
	v_lshl_add_u64 v[224:225], s[42:43], 0, v[136:137]
	ds_read_b128 v[184:187], v166 offset:32768
	ds_read_b128 v[188:191], v166 offset:33792
	ds_read_b128 v[192:195], v166 offset:34816
	ds_read_b128 v[196:199], v166 offset:35840
	ds_read_b128 v[200:203], v166 offset:36864
	ds_read_b128 v[204:207], v166 offset:37888
	ds_read_b128 v[208:211], v166 offset:38912
	ds_read_b128 v[212:215], v166 offset:39936
	global_load_lds_dwordx4 v[224:225], off
	v_lshl_add_u64 v[224:225], s[42:43], 0, v[132:133]
	s_mov_b32 m0, s49
	s_nop 0
	global_load_lds_dwordx4 v[224:225], off
	s_waitcnt vmcnt(8)
	s_waitcnt lgkmcnt(0)
	s_barrier
	s_setprio 1
	s_waitcnt lgkmcnt(0)
	v_mfma_f32_16x16x32_bf16 v[126:129], v[146:149], v[184:187], v[126:129]
	v_mfma_f32_16x16x32_bf16 v[122:125], v[154:157], v[184:187], v[122:125]
	v_mfma_f32_16x16x32_bf16 v[118:121], v[146:149], v[192:195], v[118:121]
	v_mfma_f32_16x16x32_bf16 v[110:113], v[154:157], v[192:195], v[110:113]
	v_mfma_f32_16x16x32_bf16 v[102:105], v[146:149], v[200:203], v[102:105]
	v_mfma_f32_16x16x32_bf16 v[94:97], v[154:157], v[200:203], v[94:97]
	v_mfma_f32_16x16x32_bf16 v[86:89], v[146:149], v[208:211], v[86:89]
	v_mfma_f32_16x16x32_bf16 v[78:81], v[154:157], v[208:211], v[78:81]
	v_mfma_f32_16x16x32_bf16 v[126:129], v[150:153], v[188:191], v[126:129]
	v_mfma_f32_16x16x32_bf16 v[122:125], v[158:161], v[188:191], v[122:125]
	v_mfma_f32_16x16x32_bf16 v[118:121], v[150:153], v[196:199], v[118:121]
	v_mfma_f32_16x16x32_bf16 v[110:113], v[158:161], v[196:199], v[110:113]
	v_mfma_f32_16x16x32_bf16 v[102:105], v[150:153], v[204:207], v[102:105]
	v_mfma_f32_16x16x32_bf16 v[94:97], v[158:161], v[204:207], v[94:97]
	v_mfma_f32_16x16x32_bf16 v[86:89], v[150:153], v[212:215], v[86:89]
	v_mfma_f32_16x16x32_bf16 v[78:81], v[158:161], v[212:215], v[78:81]
	s_setprio 0
	s_setprio 1
	v_mfma_f32_16x16x32_bf16 v[114:117], v[168:171], v[184:187], v[114:117]
	v_mfma_f32_16x16x32_bf16 v[106:109], v[176:179], v[184:187], v[106:109]
	v_mfma_f32_16x16x32_bf16 v[98:101], v[168:171], v[192:195], v[98:101]
	v_mfma_f32_16x16x32_bf16 v[90:93], v[176:179], v[192:195], v[90:93]
	v_mfma_f32_16x16x32_bf16 v[82:85], v[168:171], v[200:203], v[82:85]
	v_mfma_f32_16x16x32_bf16 v[74:77], v[176:179], v[200:203], v[74:77]
	v_mfma_f32_16x16x32_bf16 v[70:73], v[168:171], v[208:211], v[70:73]
	v_mfma_f32_16x16x32_bf16 v[66:69], v[176:179], v[208:211], v[66:69]
	v_mfma_f32_16x16x32_bf16 v[114:117], v[172:175], v[188:191], v[114:117]
	v_mfma_f32_16x16x32_bf16 v[106:109], v[180:183], v[188:191], v[106:109]
	v_mfma_f32_16x16x32_bf16 v[98:101], v[172:175], v[196:199], v[98:101]
	v_mfma_f32_16x16x32_bf16 v[90:93], v[180:183], v[196:199], v[90:93]
	v_mfma_f32_16x16x32_bf16 v[82:85], v[172:175], v[204:207], v[82:85]
	v_mfma_f32_16x16x32_bf16 v[74:77], v[180:183], v[204:207], v[74:77]
	v_mfma_f32_16x16x32_bf16 v[70:73], v[172:175], v[212:215], v[70:73]
	v_mfma_f32_16x16x32_bf16 v[66:69], v[180:183], v[212:215], v[66:69]
	s_setprio 0
	s_barrier
	s_add_i32 s42, s67, s33
	v_lshl_add_u64 v[216:217], v[216:217], 0, s[12:13]
	s_mov_b32 m0, s42
	ds_read_b128 v[184:187], v166 offset:49152
	ds_read_b128 v[188:191], v166 offset:50176
	ds_read_b128 v[192:195], v166 offset:51200
	ds_read_b128 v[196:199], v166 offset:52224
	ds_read_b128 v[200:203], v166 offset:53248
	ds_read_b128 v[204:207], v166 offset:54272
	ds_read_b128 v[208:211], v166 offset:55296
	ds_read_b128 v[212:215], v166 offset:56320
	global_load_lds_dwordx4 v[216:217], off
	s_add_i32 m0, s42, 0x2000
	s_add_u32 s40, s40, 0x80080
	v_lshl_add_u64 v[216:217], v[218:219], 0, s[12:13]
	s_addc_u32 s41, s41, 0
	s_add_i32 s42, s68, s33
	global_load_lds_dwordx4 v[216:217], off
	v_lshl_add_u64 v[216:217], s[40:41], 0, v[134:135]
	s_mov_b32 m0, s42
	s_nop 0
	global_load_lds_dwordx4 v[216:217], off
	v_lshl_add_u64 v[216:217], s[40:41], 0, v[130:131]
	s_add_i32 m0, s42, 0x2000
	s_nop 0
	global_load_lds_dwordx4 v[216:217], off
	v_lshl_add_u64 v[216:217], v[220:221], 0, s[12:13]
	s_mov_b32 m0, s53
	s_nop 0
	global_load_lds_dwordx4 v[216:217], off
	v_lshl_add_u64 v[216:217], v[222:223], 0, s[12:13]
	s_mov_b32 m0, s54
	s_nop 0
	global_load_lds_dwordx4 v[216:217], off
	s_waitcnt vmcnt(8)
	s_waitcnt lgkmcnt(0)
	s_barrier
	s_setprio 1
	s_waitcnt lgkmcnt(0)
	v_mfma_f32_16x16x32_bf16 v[62:65], v[146:149], v[184:187], v[62:65]
	v_mfma_f32_16x16x32_bf16 v[58:61], v[154:157], v[184:187], v[58:61]
	v_mfma_f32_16x16x32_bf16 v[54:57], v[146:149], v[192:195], v[54:57]
	v_mfma_f32_16x16x32_bf16 v[46:49], v[154:157], v[192:195], v[46:49]
	v_mfma_f32_16x16x32_bf16 v[38:41], v[146:149], v[200:203], v[38:41]
	v_mfma_f32_16x16x32_bf16 v[30:33], v[154:157], v[200:203], v[30:33]
	v_mfma_f32_16x16x32_bf16 v[22:25], v[146:149], v[208:211], v[22:25]
	v_mfma_f32_16x16x32_bf16 v[14:17], v[154:157], v[208:211], v[14:17]
	v_mfma_f32_16x16x32_bf16 v[62:65], v[150:153], v[188:191], v[62:65]
	v_mfma_f32_16x16x32_bf16 v[58:61], v[158:161], v[188:191], v[58:61]
	v_mfma_f32_16x16x32_bf16 v[54:57], v[150:153], v[196:199], v[54:57]
	v_mfma_f32_16x16x32_bf16 v[46:49], v[158:161], v[196:199], v[46:49]
	v_mfma_f32_16x16x32_bf16 v[38:41], v[150:153], v[204:207], v[38:41]
	v_mfma_f32_16x16x32_bf16 v[30:33], v[158:161], v[204:207], v[30:33]
	v_mfma_f32_16x16x32_bf16 v[22:25], v[150:153], v[212:215], v[22:25]
	v_mfma_f32_16x16x32_bf16 v[14:17], v[158:161], v[212:215], v[14:17]
	s_setprio 0
	s_setprio 1
	v_mfma_f32_16x16x32_bf16 v[50:53], v[168:171], v[184:187], v[50:53]
	v_mfma_f32_16x16x32_bf16 v[42:45], v[176:179], v[184:187], v[42:45]
	v_mfma_f32_16x16x32_bf16 v[34:37], v[168:171], v[192:195], v[34:37]
	v_mfma_f32_16x16x32_bf16 v[26:29], v[176:179], v[192:195], v[26:29]
	v_mfma_f32_16x16x32_bf16 v[18:21], v[168:171], v[200:203], v[18:21]
	v_mfma_f32_16x16x32_bf16 v[10:13], v[176:179], v[200:203], v[10:13]
	v_mfma_f32_16x16x32_bf16 v[6:9], v[168:171], v[208:211], v[6:9]
	v_mfma_f32_16x16x32_bf16 v[2:5], v[176:179], v[208:211], v[2:5]
	v_mfma_f32_16x16x32_bf16 v[50:53], v[172:175], v[188:191], v[50:53]
	v_mfma_f32_16x16x32_bf16 v[42:45], v[180:183], v[188:191], v[42:45]
	v_mfma_f32_16x16x32_bf16 v[34:37], v[172:175], v[196:199], v[34:37]
	v_mfma_f32_16x16x32_bf16 v[26:29], v[180:183], v[196:199], v[26:29]
	v_mfma_f32_16x16x32_bf16 v[18:21], v[172:175], v[204:207], v[18:21]
	v_mfma_f32_16x16x32_bf16 v[10:13], v[180:183], v[204:207], v[10:13]
	v_mfma_f32_16x16x32_bf16 v[6:9], v[172:175], v[212:215], v[6:9]
	v_mfma_f32_16x16x32_bf16 v[2:5], v[180:183], v[212:215], v[2:5]
	s_setprio 0
	s_barrier
	s_add_i32 s66, s66, 2
	s_add_u32 s8, s8, 0x100
	s_addc_u32 s9, s9, 0
	s_add_u32 s64, s64, 0x100
	s_addc_u32 s65, s65, 0
	s_cmp_gt_u32 s66, 29
	s_cbranch_scc0 .LBB0_3201
	s_and_b64 vcc, exec, s[14:15]
	s_cbranch_vccz .LBB0_3204
	s_barrier
